# LoRA-GEMM bf16 epilogue stores transposed across lanes, lane constants computed once at the first store (on v109)
# baseline (speedup 1.0000x reference)
; __device__ __forceinline__ unsigned cvt_pk_bf16(float lo, float hi) { unsigned r; asm volatile("v_cvt_pk_bf16_f32 %0, %1, %2" : "=v"(r) : "v"(lo), "v"(hi)); return r; }
;   DI void operator()(const pg8::f32x4 (&acc)[2][2][4][2], const pg8::Unit& u, int wr, int wc, int fr, int fq) const {
;     const int row0 = u.pm * 256 + wr * 64 + fr, cl = wc * 32 + 8 * fq;
;     const int kind = u.pn;
;     bfr* base = RW + (size_t)kind * MR * 256;
;     const float osc = (kind < 2) ? 0.6065306597126334f : 1.f;
; #pragma unroll
;     for (int bj = 0; bj < 2; ++bj) {
;       const int c0 = cl + bj * 128;
;       float bias[8];
; #pragma unroll
;       for (int q = 0; q < 8; ++q) bias[q] = (kind < 2) ? w0[kind * 256 + c0 + q] : ((kind < 4) ? a0[(kind - 2) * 256 + c0 + q] : 0.f);
; #pragma unroll
;       for (int ai = 0; ai < 2; ++ai)
; #pragma unroll
;         for (int m = 0; m < 4; ++m) {
;           float o[8];
; #pragma unroll
;           for (int n = 0; n < 2; ++n)
; #pragma unroll
;             for (int e = 0; e < 4; ++e) {
;               const float x = acc[ai][bj][m][n][e] + bias[n * 4 + e];
;               const float sg = osc * __builtin_amdgcn_rcpf(1.f + __expf(-x));
;               o[n * 4 + e] = (kind < 4) ? sg : x;
;             }
;           u32x4 w; w.x = pg8::cvt_pk_bf16(o[0], o[1]); w.y = pg8::cvt_pk_bf16(o[2], o[3]); w.z = pg8::cvt_pk_bf16(o[4], o[5]); w.w = pg8::cvt_pk_bf16(o[6], o[7]);
;           *(u32x4*)(base + (size_t)(row0 + ai * 128 + m * 16) * 256 + c0) = w;
;         }
;     }
;   }
.LBB0_358:
	s_waitcnt vmcnt(0)
	v_add_f32_e32 v124, v124, v159
	v_mul_f32_e32 v143, 0xbfb8aa3b, v124
	v_exp_f32_e32 v143, v143
	v_mov_b32_e32 v140, 0x3f1b4598
	v_cndmask_b32_e64 v149, 1.0, v140, s[4:5]
	v_add_f32_e32 v125, v125, v157
	v_add_f32_e32 v143, 1.0, v143
	v_rcp_f32_e32 v143, v143
	v_add_f32_e32 v126, v126, v158
	v_add_f32_e32 v127, v127, v155
	v_add_f32_e32 v120, v120, v156
	v_mul_f32_e32 v143, v149, v143
	v_cndmask_b32_e64 v124, v124, v143, s[2:3]
	v_mul_f32_e32 v143, 0xbfb8aa3b, v125
	v_exp_f32_e32 v143, v143
	v_add_f32_e32 v121, v121, v151
	v_add_f32_e32 v122, v122, v154
	v_lshl_add_u32 v142, s46, 8, v144
	v_add_f32_e32 v143, 1.0, v143
	v_rcp_f32_e32 v143, v143
	v_mad_i64_i32 v[140:141], s[46:47], s45, v189, v[134:135]
	v_add_f32_e32 v116, v116, v159
	v_mul_f32_e32 v143, v149, v143
	v_cndmask_b32_e64 v125, v125, v143, s[2:3]
	v_mul_f32_e32 v143, 0xbfb8aa3b, v126
	v_exp_f32_e32 v143, v143
	v_add_f32_e32 v117, v117, v157
	v_add_f32_e32 v118, v118, v158
	v_add_f32_e32 v119, v119, v155
	v_add_f32_e32 v143, 1.0, v143
	v_rcp_f32_e32 v143, v143
	v_add_f32_e32 v112, v112, v156
	v_add_f32_e32 v113, v113, v151
	v_add_f32_e32 v114, v114, v154
	v_mul_f32_e32 v143, v149, v143
	v_cndmask_b32_e64 v126, v126, v143, s[2:3]
	v_mul_f32_e32 v143, 0xbfb8aa3b, v127
	v_exp_f32_e32 v143, v143
	v_add_f32_e32 v108, v108, v159
	v_add_f32_e32 v109, v109, v157
	v_add_f32_e32 v110, v110, v158
	v_add_f32_e32 v143, 1.0, v143
	v_rcp_f32_e32 v143, v143
	v_add_f32_e32 v111, v111, v155
	v_add_f32_e32 v104, v104, v156
	v_add_f32_e32 v105, v105, v151
	v_mul_f32_e32 v143, v149, v143
	v_cndmask_b32_e64 v127, v127, v143, s[2:3]
	v_mul_f32_e32 v143, 0xbfb8aa3b, v120
	v_exp_f32_e32 v143, v143
	v_add_f32_e32 v106, v106, v154
	v_add_f32_e32 v100, v100, v159
	v_add_f32_e32 v101, v101, v157
	v_add_f32_e32 v143, 1.0, v143
	v_rcp_f32_e32 v143, v143
	v_add_f32_e32 v102, v102, v158
	v_add_f32_e32 v103, v103, v155
	v_add_f32_e32 v96, v96, v156
	v_mul_f32_e32 v143, v149, v143
	v_cndmask_b32_e64 v120, v120, v143, s[2:3]
	v_mul_f32_e32 v143, 0xbfb8aa3b, v121
	v_exp_f32_e32 v143, v143
	v_add_f32_e32 v97, v97, v151
	v_add_f32_e32 v98, v98, v154
	v_add_f32_e32 v92, v92, v159
	v_add_f32_e32 v143, 1.0, v143
	v_rcp_f32_e32 v143, v143
	v_add_f32_e32 v93, v93, v157
	v_add_f32_e32 v94, v94, v158
	v_add_f32_e32 v95, v95, v155
	v_mul_f32_e32 v143, v149, v143
	v_cndmask_b32_e64 v121, v121, v143, s[2:3]
	v_mul_f32_e32 v143, 0xbfb8aa3b, v122
	v_exp_f32_e32 v143, v143
	v_add_f32_e32 v88, v88, v156
	s_mov_b32 s45, 0x10000
	v_add_f32_e32 v84, v84, v159
	v_add_f32_e32 v143, 1.0, v143
	v_rcp_f32_e32 v143, v143
	v_add_f32_e32 v85, v85, v157
	v_add_f32_e32 v86, v86, v158
	v_add_f32_e32 v87, v87, v155
	v_mul_f32_e32 v143, v149, v143
	v_cndmask_b32_e64 v143, v122, v143, s[2:3]
	v_add_f32_e32 v122, v123, v150
	v_mul_f32_e32 v123, 0xbfb8aa3b, v122
	v_exp_f32_e32 v123, v123
	v_add_f32_e32 v80, v80, v156
	v_add_f32_e32 v76, v76, v159
	v_add_f32_e32 v77, v77, v157
	v_add_f32_e32 v123, 1.0, v123
	v_rcp_f32_e32 v123, v123
	v_add_f32_e32 v78, v78, v158
	v_add_f32_e32 v79, v79, v155
	v_add_f32_e32 v72, v72, v156
	v_mul_f32_e32 v123, v149, v123
	v_cndmask_b32_e64 v160, v122, v123, s[2:3]
	v_cvt_pk_bf16_f32 v122, v124, v125
	v_cvt_pk_bf16_f32 v123, v126, v127
	v_cvt_pk_bf16_f32 v124, v120, v121
	v_cvt_pk_bf16_f32 v125, v143, v160
	v_ashrrev_i32_e32 v143, 31, v142
	v_lshlrev_b64 v[120:121], 9, v[142:143]
	v_lshl_add_u64 v[120:121], v[140:141], 0, v[120:121]
	v_and_b32_e32 v250, 63, v182
	v_lshrrev_b32_e32 v251, 2, v250
	v_and_b32_e32 v248, 3, v250
	v_lshlrev_b32_e32 v249, 4, v248
	v_lshl_add_u32 v248, v248, 4, v251
	v_lshlrev_b32_e32 v248, 2, v248
	v_lshl_add_u32 v249, v251, 9, v249
	v_and_b32_e32 v251, 15, v250
	v_lshrrev_b32_e32 v250, 4, v250
	v_lshlrev_b32_e32 v251, 9, v251
	v_lshl_add_u32 v251, v250, 4, v251
	v_sub_u32_e32 v249, v249, v251
	ds_bpermute_b32 v244, v248, v122
	ds_bpermute_b32 v245, v248, v123
	ds_bpermute_b32 v246, v248, v124
	ds_bpermute_b32 v247, v248, v125
	v_ashrrev_i32_e32 v251, 31, v249
	v_add_co_u32_e64 v250, s[98:99], v120, v249
	s_nop 1
	v_addc_co_u32_e64 v251, s[98:99], v121, v251, s[98:99]
	s_waitcnt lgkmcnt(0)
	global_store_dwordx4 v[250:251], v[244:247], off
	v_add_f32_e32 v68, v68, v159
	v_add_f32_e32 v69, v69, v157
	v_mul_f32_e32 v122, 0xbfb8aa3b, v116
	v_exp_f32_e32 v122, v122
	v_add_f32_e32 v70, v70, v158
	v_add_f32_e32 v71, v71, v155
	v_add_f32_e32 v64, v64, v156
	v_add_f32_e32 v122, 1.0, v122
	v_rcp_f32_e32 v122, v122
	s_nop 0
	v_mul_f32_e32 v122, v149, v122
	v_cndmask_b32_e64 v116, v116, v122, s[2:3]
	v_mul_f32_e32 v122, 0xbfb8aa3b, v117
	v_exp_f32_e32 v122, v122
	s_nop 0
	v_add_f32_e32 v122, 1.0, v122
	v_rcp_f32_e32 v122, v122
	s_nop 0
	v_mul_f32_e32 v122, v149, v122
	v_cndmask_b32_e64 v117, v117, v122, s[2:3]
	v_mul_f32_e32 v122, 0xbfb8aa3b, v118
	v_exp_f32_e32 v122, v122
	s_nop 0
	v_add_f32_e32 v122, 1.0, v122
	v_rcp_f32_e32 v122, v122
	s_nop 0
	v_mul_f32_e32 v122, v149, v122
	v_cndmask_b32_e64 v118, v118, v122, s[2:3]
	v_mul_f32_e32 v122, 0xbfb8aa3b, v119
	v_exp_f32_e32 v122, v122
	s_nop 0
	v_add_f32_e32 v122, 1.0, v122
	v_rcp_f32_e32 v122, v122
	s_nop 0
	v_mul_f32_e32 v122, v149, v122
	v_cndmask_b32_e64 v119, v119, v122, s[2:3]
	v_mul_f32_e32 v122, 0xbfb8aa3b, v112
	v_exp_f32_e32 v122, v122
	s_nop 0
	v_add_f32_e32 v122, 1.0, v122
	v_rcp_f32_e32 v122, v122
	s_nop 0
	v_mul_f32_e32 v122, v149, v122
	v_cndmask_b32_e64 v112, v112, v122, s[2:3]
	v_mul_f32_e32 v122, 0xbfb8aa3b, v113
	v_exp_f32_e32 v122, v122
	s_nop 0
	v_add_f32_e32 v122, 1.0, v122
	v_rcp_f32_e32 v122, v122
	s_nop 0
	v_mul_f32_e32 v122, v149, v122
	v_cndmask_b32_e64 v113, v113, v122, s[2:3]
	v_mul_f32_e32 v122, 0xbfb8aa3b, v114
	v_exp_f32_e32 v122, v122
	s_nop 0
	v_add_f32_e32 v122, 1.0, v122
	v_rcp_f32_e32 v122, v122
	s_nop 0
	v_mul_f32_e32 v122, v149, v122
	v_cndmask_b32_e64 v122, v114, v122, s[2:3]
	v_add_f32_e32 v114, v115, v150
	v_mul_f32_e32 v115, 0xbfb8aa3b, v114
	v_exp_f32_e32 v115, v115
	s_nop 0
	v_add_f32_e32 v115, 1.0, v115
	v_rcp_f32_e32 v115, v115
	s_nop 0
	v_mul_f32_e32 v115, v149, v115
	v_cndmask_b32_e64 v123, v114, v115, s[2:3]
	v_cvt_pk_bf16_f32 v114, v116, v117
	v_cvt_pk_bf16_f32 v115, v118, v119
	v_cvt_pk_bf16_f32 v116, v112, v113
	v_or_b32_e32 v112, 16, v142
	v_ashrrev_i32_e32 v113, 31, v112
	v_lshlrev_b64 v[112:113], 9, v[112:113]
	v_lshl_add_u64 v[112:113], v[140:141], 0, v[112:113]
	v_cvt_pk_bf16_f32 v117, v122, v123
	ds_bpermute_b32 v244, v248, v114
	ds_bpermute_b32 v245, v248, v115
	ds_bpermute_b32 v246, v248, v116
	ds_bpermute_b32 v247, v248, v117
	v_ashrrev_i32_e32 v251, 31, v249
	v_add_co_u32_e64 v250, s[98:99], v112, v249
	s_nop 1
	v_addc_co_u32_e64 v251, s[98:99], v113, v251, s[98:99]
	s_waitcnt lgkmcnt(0)
; __device__ __forceinline__ unsigned cvt_pk_bf16(float lo, float hi) { unsigned r; asm volatile("v_cvt_pk_bf16_f32 %0, %1, %2" : "=v"(r) : "v"(lo), "v"(hi)); return r; }
;   DI void operator()(const pg8::f32x4 (&acc)[2][2][4][2], const pg8::Unit& u, int wr, int wc, int fr, int fq) const {
;     const int row0 = u.pm * 256 + wr * 64 + fr, cl = wc * 32 + 8 * fq;
;     const int kind = u.pn;
;     bfr* base = RW + (size_t)kind * MR * 256;
;     const float osc = (kind < 2) ? 0.6065306597126334f : 1.f;
; #pragma unroll
;     for (int bj = 0; bj < 2; ++bj) {
;       const int c0 = cl + bj * 128;
;       float bias[8];
; #pragma unroll
;       for (int q = 0; q < 8; ++q) bias[q] = (kind < 2) ? w0[kind * 256 + c0 + q] : ((kind < 4) ? a0[(kind - 2) * 256 + c0 + q] : 0.f);
; #pragma unroll
;       for (int ai = 0; ai < 2; ++ai)
; #pragma unroll
;         for (int m = 0; m < 4; ++m) {
;           float o[8];
; #pragma unroll
;           for (int n = 0; n < 2; ++n)
; #pragma unroll
;             for (int e = 0; e < 4; ++e) {
;               const float x = acc[ai][bj][m][n][e] + bias[n * 4 + e];
;               const float sg = osc * __builtin_amdgcn_rcpf(1.f + __expf(-x));
;               o[n * 4 + e] = (kind < 4) ? sg : x;
;             }
;           u32x4 w; w.x = pg8::cvt_pk_bf16(o[0], o[1]); w.y = pg8::cvt_pk_bf16(o[2], o[3]); w.z = pg8::cvt_pk_bf16(o[4], o[5]); w.w = pg8::cvt_pk_bf16(o[6], o[7]);
;           *(u32x4*)(base + (size_t)(row0 + ai * 128 + m * 16) * 256 + c0) = w;
;         }
;     }
;   }
	global_store_dwordx4 v[250:251], v[244:247], off
	s_nop 1
	v_mul_f32_e32 v114, 0xbfb8aa3b, v108
	v_exp_f32_e32 v114, v114
	s_nop 0
	v_add_f32_e32 v114, 1.0, v114
	v_rcp_f32_e32 v114, v114
	s_nop 0
	v_mul_f32_e32 v114, v149, v114
	v_cndmask_b32_e64 v108, v108, v114, s[2:3]
	v_mul_f32_e32 v114, 0xbfb8aa3b, v109
	v_exp_f32_e32 v114, v114
	s_nop 0
	v_add_f32_e32 v114, 1.0, v114
	v_rcp_f32_e32 v114, v114
	s_nop 0
	v_mul_f32_e32 v114, v149, v114
	v_cndmask_b32_e64 v109, v109, v114, s[2:3]
	v_mul_f32_e32 v114, 0xbfb8aa3b, v110
	v_exp_f32_e32 v114, v114
	s_nop 0
	v_add_f32_e32 v114, 1.0, v114
	v_rcp_f32_e32 v114, v114
	s_nop 0
	v_mul_f32_e32 v114, v149, v114
	v_cndmask_b32_e64 v110, v110, v114, s[2:3]
	v_mul_f32_e32 v114, 0xbfb8aa3b, v111
	v_exp_f32_e32 v114, v114
	s_nop 0
	v_add_f32_e32 v114, 1.0, v114
	v_rcp_f32_e32 v114, v114
	s_nop 0
	v_mul_f32_e32 v114, v149, v114
	v_cndmask_b32_e64 v111, v111, v114, s[2:3]
	v_mul_f32_e32 v114, 0xbfb8aa3b, v104
	v_exp_f32_e32 v114, v114
	s_nop 0
	v_add_f32_e32 v114, 1.0, v114
	v_rcp_f32_e32 v114, v114
	s_nop 0
	v_mul_f32_e32 v114, v149, v114
	v_cndmask_b32_e64 v104, v104, v114, s[2:3]
	v_mul_f32_e32 v114, 0xbfb8aa3b, v105
	v_exp_f32_e32 v114, v114
	s_nop 0
	v_add_f32_e32 v114, 1.0, v114
	v_rcp_f32_e32 v114, v114
	s_nop 0
	v_mul_f32_e32 v114, v149, v114
	v_cndmask_b32_e64 v105, v105, v114, s[2:3]
	v_mul_f32_e32 v114, 0xbfb8aa3b, v106
	v_exp_f32_e32 v114, v114
	s_nop 0
	v_add_f32_e32 v114, 1.0, v114
	v_rcp_f32_e32 v114, v114
	s_nop 0
	v_mul_f32_e32 v114, v149, v114
	v_cndmask_b32_e64 v114, v106, v114, s[2:3]
	v_add_f32_e32 v106, v107, v150
	v_mul_f32_e32 v107, 0xbfb8aa3b, v106
	v_exp_f32_e32 v107, v107
	s_nop 0
	v_add_f32_e32 v107, 1.0, v107
	v_rcp_f32_e32 v107, v107
	s_nop 0
	v_mul_f32_e32 v107, v149, v107
	v_cndmask_b32_e64 v115, v106, v107, s[2:3]
	v_cvt_pk_bf16_f32 v106, v108, v109
	v_cvt_pk_bf16_f32 v107, v110, v111
	v_cvt_pk_bf16_f32 v108, v104, v105
	v_or_b32_e32 v104, 32, v142
	v_ashrrev_i32_e32 v105, 31, v104
	v_lshlrev_b64 v[104:105], 9, v[104:105]
	v_lshl_add_u64 v[104:105], v[140:141], 0, v[104:105]
	v_cvt_pk_bf16_f32 v109, v114, v115
	ds_bpermute_b32 v244, v248, v106
	ds_bpermute_b32 v245, v248, v107
	ds_bpermute_b32 v246, v248, v108
	ds_bpermute_b32 v247, v248, v109
	v_ashrrev_i32_e32 v251, 31, v249
	v_add_co_u32_e64 v250, s[98:99], v104, v249
	s_nop 1
	v_addc_co_u32_e64 v251, s[98:99], v105, v251, s[98:99]
	s_waitcnt lgkmcnt(0)
	global_store_dwordx4 v[250:251], v[244:247], off
	s_nop 1
	v_mul_f32_e32 v106, 0xbfb8aa3b, v100
	v_exp_f32_e32 v106, v106
	s_nop 0
	v_add_f32_e32 v106, 1.0, v106
	v_rcp_f32_e32 v106, v106
	s_nop 0
	v_mul_f32_e32 v106, v149, v106
	v_cndmask_b32_e64 v100, v100, v106, s[2:3]
	v_mul_f32_e32 v106, 0xbfb8aa3b, v101
	v_exp_f32_e32 v106, v106
	s_nop 0
	v_add_f32_e32 v106, 1.0, v106
	v_rcp_f32_e32 v106, v106
	s_nop 0
	v_mul_f32_e32 v106, v149, v106
	v_cndmask_b32_e64 v101, v101, v106, s[2:3]
	v_mul_f32_e32 v106, 0xbfb8aa3b, v102
	v_exp_f32_e32 v106, v106
	s_nop 0
	v_add_f32_e32 v106, 1.0, v106
	v_rcp_f32_e32 v106, v106
	s_nop 0
	v_mul_f32_e32 v106, v149, v106
	v_cndmask_b32_e64 v102, v102, v106, s[2:3]
	v_mul_f32_e32 v106, 0xbfb8aa3b, v103
	v_exp_f32_e32 v106, v106
	s_nop 0
	v_add_f32_e32 v106, 1.0, v106
	v_rcp_f32_e32 v106, v106
	s_nop 0
	v_mul_f32_e32 v106, v149, v106
	v_cndmask_b32_e64 v103, v103, v106, s[2:3]
	v_mul_f32_e32 v106, 0xbfb8aa3b, v96
	v_exp_f32_e32 v106, v106
	s_nop 0
	v_add_f32_e32 v106, 1.0, v106
	v_rcp_f32_e32 v106, v106
	s_nop 0
	v_mul_f32_e32 v106, v149, v106
	v_cndmask_b32_e64 v96, v96, v106, s[2:3]
	v_mul_f32_e32 v106, 0xbfb8aa3b, v97
	v_exp_f32_e32 v106, v106
	s_nop 0
	v_add_f32_e32 v106, 1.0, v106
	v_rcp_f32_e32 v106, v106
	s_nop 0
	v_mul_f32_e32 v106, v149, v106
	v_cndmask_b32_e64 v97, v97, v106, s[2:3]
	v_mul_f32_e32 v106, 0xbfb8aa3b, v98
	v_exp_f32_e32 v106, v106
	s_nop 0
	v_add_f32_e32 v106, 1.0, v106
	v_rcp_f32_e32 v106, v106
	s_nop 0
	v_mul_f32_e32 v106, v149, v106
	v_cndmask_b32_e64 v106, v98, v106, s[2:3]
	v_add_f32_e32 v98, v99, v150
	v_mul_f32_e32 v99, 0xbfb8aa3b, v98
	v_exp_f32_e32 v99, v99
	s_nop 0
	v_add_f32_e32 v99, 1.0, v99
	v_rcp_f32_e32 v99, v99
	s_nop 0
	v_mul_f32_e32 v99, v149, v99
	v_cndmask_b32_e64 v107, v98, v99, s[2:3]
	v_cvt_pk_bf16_f32 v98, v100, v101
	v_cvt_pk_bf16_f32 v99, v102, v103
	v_cvt_pk_bf16_f32 v100, v96, v97
	v_or_b32_e32 v96, 48, v142
	v_ashrrev_i32_e32 v97, 31, v96
	v_lshlrev_b64 v[96:97], 9, v[96:97]
	v_lshl_add_u64 v[96:97], v[140:141], 0, v[96:97]
	v_cvt_pk_bf16_f32 v101, v106, v107
	ds_bpermute_b32 v244, v248, v98
	ds_bpermute_b32 v245, v248, v99
	ds_bpermute_b32 v246, v248, v100
	ds_bpermute_b32 v247, v248, v101
	v_ashrrev_i32_e32 v251, 31, v249
	v_add_co_u32_e64 v250, s[98:99], v96, v249
	s_nop 1
	v_addc_co_u32_e64 v251, s[98:99], v97, v251, s[98:99]
	s_waitcnt lgkmcnt(0)
; __device__ __forceinline__ unsigned cvt_pk_bf16(float lo, float hi) { unsigned r; asm volatile("v_cvt_pk_bf16_f32 %0, %1, %2" : "=v"(r) : "v"(lo), "v"(hi)); return r; }
;   DI void operator()(const pg8::f32x4 (&acc)[2][2][4][2], const pg8::Unit& u, int wr, int wc, int fr, int fq) const {
;     const int row0 = u.pm * 256 + wr * 64 + fr, cl = wc * 32 + 8 * fq;
;     const int kind = u.pn;
;     bfr* base = RW + (size_t)kind * MR * 256;
;     const float osc = (kind < 2) ? 0.6065306597126334f : 1.f;
; #pragma unroll
;     for (int bj = 0; bj < 2; ++bj) {
;       const int c0 = cl + bj * 128;
;       float bias[8];
; #pragma unroll
;       for (int q = 0; q < 8; ++q) bias[q] = (kind < 2) ? w0[kind * 256 + c0 + q] : ((kind < 4) ? a0[(kind - 2) * 256 + c0 + q] : 0.f);
; #pragma unroll
;       for (int ai = 0; ai < 2; ++ai)
; #pragma unroll
;         for (int m = 0; m < 4; ++m) {
;           float o[8];
; #pragma unroll
;           for (int n = 0; n < 2; ++n)
; #pragma unroll
;             for (int e = 0; e < 4; ++e) {
;               const float x = acc[ai][bj][m][n][e] + bias[n * 4 + e];
;               const float sg = osc * __builtin_amdgcn_rcpf(1.f + __expf(-x));
;               o[n * 4 + e] = (kind < 4) ? sg : x;
;             }
;           u32x4 w; w.x = pg8::cvt_pk_bf16(o[0], o[1]); w.y = pg8::cvt_pk_bf16(o[2], o[3]); w.z = pg8::cvt_pk_bf16(o[4], o[5]); w.w = pg8::cvt_pk_bf16(o[6], o[7]);
;           *(u32x4*)(base + (size_t)(row0 + ai * 128 + m * 16) * 256 + c0) = w;
;         }
;     }
;   }
	global_store_dwordx4 v[250:251], v[244:247], off
	s_nop 1
	v_mul_f32_e32 v98, 0xbfb8aa3b, v92
	v_exp_f32_e32 v98, v98
	s_nop 0
	v_add_f32_e32 v98, 1.0, v98
	v_rcp_f32_e32 v98, v98
	s_nop 0
	v_mul_f32_e32 v98, v149, v98
	v_cndmask_b32_e64 v92, v92, v98, s[2:3]
	v_mul_f32_e32 v98, 0xbfb8aa3b, v93
	v_exp_f32_e32 v98, v98
	s_nop 0
	v_add_f32_e32 v98, 1.0, v98
	v_rcp_f32_e32 v98, v98
	s_nop 0
	v_mul_f32_e32 v98, v149, v98
	v_cndmask_b32_e64 v93, v93, v98, s[2:3]
	v_mul_f32_e32 v98, 0xbfb8aa3b, v94
	v_exp_f32_e32 v98, v98
	s_nop 0
	v_add_f32_e32 v98, 1.0, v98
	v_rcp_f32_e32 v98, v98
	s_nop 0
	v_mul_f32_e32 v98, v149, v98
	v_cndmask_b32_e64 v94, v94, v98, s[2:3]
	v_mul_f32_e32 v98, 0xbfb8aa3b, v95
	v_exp_f32_e32 v98, v98
	s_nop 0
	v_add_f32_e32 v98, 1.0, v98
	v_rcp_f32_e32 v98, v98
	s_nop 0
	v_mul_f32_e32 v98, v149, v98
	v_cndmask_b32_e64 v95, v95, v98, s[2:3]
	v_mul_f32_e32 v98, 0xbfb8aa3b, v88
	v_exp_f32_e32 v98, v98
	s_nop 0
	v_add_f32_e32 v98, 1.0, v98
	v_rcp_f32_e32 v98, v98
	s_nop 0
	v_mul_f32_e32 v98, v149, v98
	v_cndmask_b32_e64 v98, v88, v98, s[2:3]
	v_add_f32_e32 v88, v89, v151
	v_mul_f32_e32 v89, 0xbfb8aa3b, v88
	v_exp_f32_e32 v89, v89
	s_nop 0
	v_add_f32_e32 v89, 1.0, v89
	v_rcp_f32_e32 v89, v89
	s_nop 0
	v_mul_f32_e32 v89, v149, v89
	v_cndmask_b32_e64 v99, v88, v89, s[2:3]
	v_add_f32_e32 v88, v90, v154
	v_mul_f32_e32 v89, 0xbfb8aa3b, v88
	v_exp_f32_e32 v89, v89
	s_nop 0
	v_add_f32_e32 v89, 1.0, v89
	v_rcp_f32_e32 v89, v89
	s_nop 0
	v_mul_f32_e32 v89, v149, v89
	v_cndmask_b32_e64 v100, v88, v89, s[2:3]
	v_add_f32_e32 v88, v91, v150
	v_mul_f32_e32 v89, 0xbfb8aa3b, v88
	v_exp_f32_e32 v89, v89
	s_nop 0
	v_add_f32_e32 v89, 1.0, v89
	v_rcp_f32_e32 v89, v89
	s_nop 0
	v_mul_f32_e32 v89, v149, v89
	v_cndmask_b32_e64 v91, v88, v89, s[2:3]
	v_cvt_pk_bf16_f32 v88, v92, v93
	v_add_co_u32_e32 v92, vcc, s45, v120
	v_cvt_pk_bf16_f32 v89, v94, v95
	v_cvt_pk_bf16_f32 v90, v98, v99
	v_cvt_pk_bf16_f32 v91, v100, v91
	s_mov_b32 s45, 0x12000
	s_nop 0
	v_addc_co_u32_e32 v93, vcc, 0, v121, vcc
	ds_bpermute_b32 v244, v248, v88
	ds_bpermute_b32 v245, v248, v89
	ds_bpermute_b32 v246, v248, v90
	ds_bpermute_b32 v247, v248, v91
	v_ashrrev_i32_e32 v251, 31, v249
	v_add_co_u32_e64 v250, s[98:99], v92, v249
	s_nop 1
	v_addc_co_u32_e64 v251, s[98:99], v93, v251, s[98:99]
	s_waitcnt lgkmcnt(0)
	global_store_dwordx4 v[250:251], v[244:247], off
	s_nop 1
	v_mul_f32_e32 v88, 0xbfb8aa3b, v84
	v_exp_f32_e32 v88, v88
	s_nop 0
	v_add_f32_e32 v88, 1.0, v88
	v_rcp_f32_e32 v88, v88
	s_nop 0
	v_mul_f32_e32 v88, v149, v88
	v_cndmask_b32_e64 v84, v84, v88, s[2:3]
	v_mul_f32_e32 v88, 0xbfb8aa3b, v85
	v_exp_f32_e32 v88, v88
	s_nop 0
	v_add_f32_e32 v88, 1.0, v88
	v_rcp_f32_e32 v88, v88
	s_nop 0
	v_mul_f32_e32 v88, v149, v88
	v_cndmask_b32_e64 v85, v85, v88, s[2:3]
	v_mul_f32_e32 v88, 0xbfb8aa3b, v86
	v_exp_f32_e32 v88, v88
	s_nop 0
	v_add_f32_e32 v88, 1.0, v88
	v_rcp_f32_e32 v88, v88
	s_nop 0
	v_mul_f32_e32 v88, v149, v88
	v_cndmask_b32_e64 v86, v86, v88, s[2:3]
	v_mul_f32_e32 v88, 0xbfb8aa3b, v87
	v_exp_f32_e32 v88, v88
	s_nop 0
	v_add_f32_e32 v88, 1.0, v88
	v_rcp_f32_e32 v88, v88
	s_nop 0
	v_mul_f32_e32 v88, v149, v88
	v_cndmask_b32_e64 v87, v87, v88, s[2:3]
	v_mul_f32_e32 v88, 0xbfb8aa3b, v80
	v_exp_f32_e32 v88, v88
	s_nop 0
	v_add_f32_e32 v88, 1.0, v88
	v_rcp_f32_e32 v88, v88
	s_nop 0
	v_mul_f32_e32 v88, v149, v88
	v_cndmask_b32_e64 v88, v80, v88, s[2:3]
	v_add_f32_e32 v80, v81, v151
	v_mul_f32_e32 v81, 0xbfb8aa3b, v80
	v_exp_f32_e32 v81, v81
	s_nop 0
	v_add_f32_e32 v81, 1.0, v81
	v_rcp_f32_e32 v81, v81
	s_nop 0
	v_mul_f32_e32 v81, v149, v81
	v_cndmask_b32_e64 v89, v80, v81, s[2:3]
	v_add_f32_e32 v80, v82, v154
	v_mul_f32_e32 v81, 0xbfb8aa3b, v80
	v_exp_f32_e32 v81, v81
	s_nop 0
	v_add_f32_e32 v81, 1.0, v81
	v_rcp_f32_e32 v81, v81
	s_nop 0
	v_mul_f32_e32 v81, v149, v81
	v_cndmask_b32_e64 v90, v80, v81, s[2:3]
	v_add_f32_e32 v80, v83, v150
	v_mul_f32_e32 v81, 0xbfb8aa3b, v80
	v_exp_f32_e32 v81, v81
	s_nop 0
	v_add_f32_e32 v81, 1.0, v81
	v_rcp_f32_e32 v81, v81
	s_nop 0
	v_mul_f32_e32 v81, v149, v81
	v_cndmask_b32_e64 v83, v80, v81, s[2:3]
	v_cvt_pk_bf16_f32 v80, v84, v85
	v_add_co_u32_e32 v84, vcc, s45, v120
	v_cvt_pk_bf16_f32 v81, v86, v87
	v_cvt_pk_bf16_f32 v82, v88, v89
	v_cvt_pk_bf16_f32 v83, v90, v83
	s_mov_b32 s45, 0x14000
	s_nop 0
	v_addc_co_u32_e32 v85, vcc, 0, v121, vcc
	ds_bpermute_b32 v244, v248, v80
	ds_bpermute_b32 v245, v248, v81
	ds_bpermute_b32 v246, v248, v82
	ds_bpermute_b32 v247, v248, v83
	v_ashrrev_i32_e32 v251, 31, v249
	v_add_co_u32_e64 v250, s[98:99], v84, v249
	s_nop 1
	v_addc_co_u32_e64 v251, s[98:99], v85, v251, s[98:99]
	s_waitcnt lgkmcnt(0)
; __device__ __forceinline__ unsigned cvt_pk_bf16(float lo, float hi) { unsigned r; asm volatile("v_cvt_pk_bf16_f32 %0, %1, %2" : "=v"(r) : "v"(lo), "v"(hi)); return r; }
;   DI void operator()(const pg8::f32x4 (&acc)[2][2][4][2], const pg8::Unit& u, int wr, int wc, int fr, int fq) const {
;     const int row0 = u.pm * 256 + wr * 64 + fr, cl = wc * 32 + 8 * fq;
;     const int kind = u.pn;
;     bfr* base = RW + (size_t)kind * MR * 256;
;     const float osc = (kind < 2) ? 0.6065306597126334f : 1.f;
; #pragma unroll
;     for (int bj = 0; bj < 2; ++bj) {
;       const int c0 = cl + bj * 128;
;       float bias[8];
; #pragma unroll
;       for (int q = 0; q < 8; ++q) bias[q] = (kind < 2) ? w0[kind * 256 + c0 + q] : ((kind < 4) ? a0[(kind - 2) * 256 + c0 + q] : 0.f);
; #pragma unroll
;       for (int ai = 0; ai < 2; ++ai)
; #pragma unroll
;         for (int m = 0; m < 4; ++m) {
;           float o[8];
; #pragma unroll
;           for (int n = 0; n < 2; ++n)
; #pragma unroll
;             for (int e = 0; e < 4; ++e) {
;               const float x = acc[ai][bj][m][n][e] + bias[n * 4 + e];
;               const float sg = osc * __builtin_amdgcn_rcpf(1.f + __expf(-x));
;               o[n * 4 + e] = (kind < 4) ? sg : x;
;             }
;           u32x4 w; w.x = pg8::cvt_pk_bf16(o[0], o[1]); w.y = pg8::cvt_pk_bf16(o[2], o[3]); w.z = pg8::cvt_pk_bf16(o[4], o[5]); w.w = pg8::cvt_pk_bf16(o[6], o[7]);
;           *(u32x4*)(base + (size_t)(row0 + ai * 128 + m * 16) * 256 + c0) = w;
;         }
;     }
;   }
	global_store_dwordx4 v[250:251], v[244:247], off
	s_nop 1
	v_mul_f32_e32 v80, 0xbfb8aa3b, v76
	v_exp_f32_e32 v80, v80
	s_nop 0
	v_add_f32_e32 v80, 1.0, v80
	v_rcp_f32_e32 v80, v80
	s_nop 0
	v_mul_f32_e32 v80, v149, v80
	v_cndmask_b32_e64 v76, v76, v80, s[2:3]
	v_mul_f32_e32 v80, 0xbfb8aa3b, v77
	v_exp_f32_e32 v80, v80
	s_nop 0
	v_add_f32_e32 v80, 1.0, v80
	v_rcp_f32_e32 v80, v80
	s_nop 0
	v_mul_f32_e32 v80, v149, v80
	v_cndmask_b32_e64 v77, v77, v80, s[2:3]
	v_mul_f32_e32 v80, 0xbfb8aa3b, v78
	v_exp_f32_e32 v80, v80
	s_nop 0
	v_add_f32_e32 v80, 1.0, v80
	v_rcp_f32_e32 v80, v80
	s_nop 0
	v_mul_f32_e32 v80, v149, v80
	v_cndmask_b32_e64 v78, v78, v80, s[2:3]
	v_mul_f32_e32 v80, 0xbfb8aa3b, v79
	v_exp_f32_e32 v80, v80
	s_nop 0
	v_add_f32_e32 v80, 1.0, v80
	v_rcp_f32_e32 v80, v80
	s_nop 0
	v_mul_f32_e32 v80, v149, v80
	v_cndmask_b32_e64 v79, v79, v80, s[2:3]
	v_mul_f32_e32 v80, 0xbfb8aa3b, v72
	v_exp_f32_e32 v80, v80
	s_nop 0
	v_add_f32_e32 v80, 1.0, v80
	v_rcp_f32_e32 v80, v80
	s_nop 0
	v_mul_f32_e32 v80, v149, v80
	v_cndmask_b32_e64 v80, v72, v80, s[2:3]
	v_add_f32_e32 v72, v73, v151
	v_mul_f32_e32 v73, 0xbfb8aa3b, v72
	v_exp_f32_e32 v73, v73
	s_nop 0
	v_add_f32_e32 v73, 1.0, v73
	v_rcp_f32_e32 v73, v73
	s_nop 0
	v_mul_f32_e32 v73, v149, v73
	v_cndmask_b32_e64 v81, v72, v73, s[2:3]
	v_add_f32_e32 v72, v74, v154
	v_mul_f32_e32 v73, 0xbfb8aa3b, v72
	v_exp_f32_e32 v73, v73
	s_nop 0
	v_add_f32_e32 v73, 1.0, v73
	v_rcp_f32_e32 v73, v73
	s_nop 0
	v_mul_f32_e32 v73, v149, v73
	v_cndmask_b32_e64 v82, v72, v73, s[2:3]
	v_add_f32_e32 v72, v75, v150
	v_mul_f32_e32 v73, 0xbfb8aa3b, v72
	v_exp_f32_e32 v73, v73
	s_nop 0
	v_add_f32_e32 v73, 1.0, v73
	v_rcp_f32_e32 v73, v73
	s_nop 0
	v_mul_f32_e32 v73, v149, v73
	v_cndmask_b32_e64 v75, v72, v73, s[2:3]
	v_cvt_pk_bf16_f32 v72, v76, v77
	v_add_co_u32_e32 v76, vcc, s45, v120
	v_cvt_pk_bf16_f32 v73, v78, v79
	v_cvt_pk_bf16_f32 v74, v80, v81
	v_cvt_pk_bf16_f32 v75, v82, v75
	v_mov_b32_e32 v79, 0
	s_nop 0
	v_addc_co_u32_e32 v77, vcc, 0, v121, vcc
	ds_bpermute_b32 v244, v248, v72
	ds_bpermute_b32 v245, v248, v73
	ds_bpermute_b32 v246, v248, v74
	ds_bpermute_b32 v247, v248, v75
	v_ashrrev_i32_e32 v251, 31, v249
	v_add_co_u32_e64 v250, s[98:99], v76, v249
	s_nop 1
	v_addc_co_u32_e64 v251, s[98:99], v77, v251, s[98:99]
	s_waitcnt lgkmcnt(0)
	global_store_dwordx4 v[250:251], v[244:247], off
	v_mov_b32_e32 v77, 0
	s_nop 0
	v_mul_f32_e32 v72, 0xbfb8aa3b, v68
	v_exp_f32_e32 v72, v72
	s_nop 0
	v_add_f32_e32 v72, 1.0, v72
	v_rcp_f32_e32 v72, v72
	s_nop 0
	v_mul_f32_e32 v72, v149, v72
	v_cndmask_b32_e64 v68, v68, v72, s[2:3]
	v_mul_f32_e32 v72, 0xbfb8aa3b, v69
	v_exp_f32_e32 v72, v72
	s_nop 0
	v_add_f32_e32 v72, 1.0, v72
	v_rcp_f32_e32 v72, v72
	s_nop 0
	v_mul_f32_e32 v72, v149, v72
	v_cndmask_b32_e64 v69, v69, v72, s[2:3]
	v_mul_f32_e32 v72, 0xbfb8aa3b, v70
	v_exp_f32_e32 v72, v72
	s_nop 0
	v_add_f32_e32 v72, 1.0, v72
	v_rcp_f32_e32 v72, v72
	s_nop 0
	v_mul_f32_e32 v72, v149, v72
	v_cndmask_b32_e64 v70, v70, v72, s[2:3]
	v_mul_f32_e32 v72, 0xbfb8aa3b, v71
	v_exp_f32_e32 v72, v72
	s_nop 0
	v_add_f32_e32 v72, 1.0, v72
	v_rcp_f32_e32 v72, v72
	s_nop 0
	v_mul_f32_e32 v72, v149, v72
	v_cndmask_b32_e64 v71, v71, v72, s[2:3]
	v_mul_f32_e32 v72, 0xbfb8aa3b, v64
	v_exp_f32_e32 v72, v72
	s_nop 0
	v_add_f32_e32 v72, 1.0, v72
	v_rcp_f32_e32 v72, v72
	s_nop 0
	v_mul_f32_e32 v72, v149, v72
	v_cndmask_b32_e64 v72, v64, v72, s[2:3]
	v_add_f32_e32 v64, v65, v151
	v_mul_f32_e32 v65, 0xbfb8aa3b, v64
	v_exp_f32_e32 v65, v65
	s_nop 0
	v_add_f32_e32 v65, 1.0, v65
	v_rcp_f32_e32 v65, v65
	s_nop 0
	v_mul_f32_e32 v65, v149, v65
	v_cndmask_b32_e64 v73, v64, v65, s[2:3]
	v_add_f32_e32 v64, v66, v154
	v_mul_f32_e32 v65, 0xbfb8aa3b, v64
	v_exp_f32_e32 v65, v65
	s_nop 0
	v_add_f32_e32 v65, 1.0, v65
	v_rcp_f32_e32 v65, v65
	s_nop 0
	v_mul_f32_e32 v65, v149, v65
	v_cndmask_b32_e64 v74, v64, v65, s[2:3]
	v_add_f32_e32 v64, v67, v150
	v_mul_f32_e32 v65, 0xbfb8aa3b, v64
	v_exp_f32_e32 v65, v65
	s_nop 0
	v_add_f32_e32 v65, 1.0, v65
	v_rcp_f32_e32 v65, v65
	s_nop 0
	v_mul_f32_e32 v65, v149, v65
	v_cndmask_b32_e64 v67, v64, v65, s[2:3]
	v_cvt_pk_bf16_f32 v64, v68, v69
	v_add_co_u32_e32 v68, vcc, 0x16000, v120
	v_cvt_pk_bf16_f32 v65, v70, v71
	v_cvt_pk_bf16_f32 v66, v72, v73
	v_cvt_pk_bf16_f32 v67, v74, v67
	s_nop 1
	v_addc_co_u32_e32 v69, vcc, 0, v121, vcc
	ds_bpermute_b32 v244, v248, v64
	ds_bpermute_b32 v245, v248, v65
	ds_bpermute_b32 v246, v248, v66
	ds_bpermute_b32 v247, v248, v67
	v_ashrrev_i32_e32 v251, 31, v249
	v_add_co_u32_e64 v250, s[98:99], v68, v249
	s_nop 1
	v_addc_co_u32_e64 v251, s[98:99], v69, v251, s[98:99]
	s_waitcnt lgkmcnt(0)
	global_store_dwordx4 v[250:251], v[244:247], off
	s_and_b64 vcc, exec, s[8:9]
	s_nop 0
	v_or_b32_e32 v64, s44, v147
	v_or_b32_e32 v65, s43, v147
	v_cndmask_b32_e64 v64, v64, v65, s[4:5]
	v_ashrrev_i32_e32 v65, 31, v64
	s_cbranch_vccnz .LBB0_366
	s_and_b64 s[44:45], s[4:5], exec
	s_cselect_b32 s43, s30, s34
	s_cselect_b32 s44, s29, s31
	v_mov_b32_e32 v66, s44
	v_mov_b32_e32 v67, s43
	v_lshl_add_u64 v[66:67], v[64:65], 2, v[66:67]
	global_load_dword v79, v[66:67], off
	s_and_b64 vcc, exec, s[8:9]
	s_cbranch_vccz .LBB0_367

; __device__ __forceinline__ unsigned cvt_pk_bf16(float lo, float hi) { unsigned r; asm volatile("v_cvt_pk_bf16_f32 %0, %1, %2" : "=v"(r) : "v"(lo), "v"(hi)); return r; }
;   DI void operator()(const pg8::f32x4 (&acc)[2][2][4][2], const pg8::Unit& u, int wr, int wc, int fr, int fq) const {
;     ...
;     for (int bj = 0; bj < 2; ++bj) {
;       const int c0 = cl + bj * 128;
;       float bias[8];
; #pragma unroll
;       for (int q = 0; q < 8; ++q) bias[q] = (kind < 2) ? w0[kind * 256 + c0 + q] : ((kind < 4) ? a0[(kind - 2) * 256 + c0 + q] : 0.f);
; #pragma unroll
;       for (int ai = 0; ai < 2; ++ai)
; #pragma unroll
;         for (int m = 0; m < 4; ++m) {
;           float o[8];
; #pragma unroll
;           for (int n = 0; n < 2; ++n)
; #pragma unroll
;             for (int e = 0; e < 4; ++e) {
;               const float x = acc[ai][bj][m][n][e] + bias[n * 4 + e];
;               const float sg = osc * __builtin_amdgcn_rcpf(1.f + __expf(-x));
;               o[n * 4 + e] = (kind < 4) ? sg : x;
;             }
;           u32x4 w; w.x = pg8::cvt_pk_bf16(o[0], o[1]); w.y = pg8::cvt_pk_bf16(o[2], o[3]); w.z = pg8::cvt_pk_bf16(o[4], o[5]); w.w = pg8::cvt_pk_bf16(o[6], o[7]);
;           *(u32x4*)(base + (size_t)(row0 + ai * 128 + m * 16) * 256 + c0) = w;
.LBB0_374:
	s_waitcnt vmcnt(0)
	v_add_f32_e32 v60, v60, v79
	v_mul_f32_e32 v80, 0xbfb8aa3b, v60
	v_exp_f32_e32 v80, v80
	v_add_f32_e32 v61, v61, v77
	v_add_f32_e32 v62, v62, v78
	v_add_f32_e32 v63, v63, v75
	v_add_f32_e32 v80, 1.0, v80
	v_rcp_f32_e32 v80, v80
	v_add_f32_e32 v56, v56, v76
	v_add_f32_e32 v52, v52, v79
	v_add_f32_e32 v53, v53, v77
	v_mul_f32_e32 v80, v149, v80
	v_cndmask_b32_e64 v60, v60, v80, s[2:3]
	v_mul_f32_e32 v80, 0xbfb8aa3b, v61
	v_exp_f32_e32 v80, v80
	v_add_f32_e32 v54, v54, v78
	v_add_f32_e32 v55, v55, v75
	v_add_f32_e32 v48, v48, v76
	v_add_f32_e32 v80, 1.0, v80
	v_rcp_f32_e32 v80, v80
	v_add_f32_e32 v44, v44, v79
	v_add_f32_e32 v45, v45, v77
	v_add_f32_e32 v46, v46, v78
	v_mul_f32_e32 v80, v149, v80
	v_cndmask_b32_e64 v61, v61, v80, s[2:3]
	v_mul_f32_e32 v80, 0xbfb8aa3b, v62
	v_exp_f32_e32 v80, v80
	v_add_f32_e32 v47, v47, v75
	v_add_f32_e32 v40, v40, v76
	v_add_f32_e32 v36, v36, v79
	v_add_f32_e32 v80, 1.0, v80
	v_rcp_f32_e32 v80, v80
	v_add_f32_e32 v37, v37, v77
	v_add_f32_e32 v38, v38, v78
	v_add_f32_e32 v39, v39, v75
	v_mul_f32_e32 v80, v149, v80
	v_cndmask_b32_e64 v62, v62, v80, s[2:3]
	v_mul_f32_e32 v80, 0xbfb8aa3b, v63
	v_exp_f32_e32 v80, v80
	v_add_f32_e32 v32, v32, v76
	v_add_f32_e32 v28, v28, v79
	v_add_f32_e32 v29, v29, v77
	v_add_f32_e32 v80, 1.0, v80
	v_rcp_f32_e32 v80, v80
	v_add_f32_e32 v30, v30, v78
	v_add_f32_e32 v31, v31, v75
	v_add_f32_e32 v24, v24, v76
	v_mul_f32_e32 v80, v149, v80
	v_cndmask_b32_e64 v63, v63, v80, s[2:3]
	v_mul_f32_e32 v80, 0xbfb8aa3b, v56
	v_exp_f32_e32 v80, v80
	s_mov_b64 s[4:5], 0x10000
	v_lshl_add_u64 v[70:71], v[120:121], 0, s[4:5]
	v_add_f32_e32 v20, v20, v79
	v_add_f32_e32 v80, 1.0, v80
	v_rcp_f32_e32 v80, v80
	v_add_f32_e32 v21, v21, v77
	v_add_f32_e32 v22, v22, v78
	v_add_f32_e32 v23, v23, v75
	v_mul_f32_e32 v80, v149, v80
	v_cndmask_b32_e64 v80, v56, v80, s[2:3]
	v_add_f32_e32 v56, v57, v73
	v_mul_f32_e32 v57, 0xbfb8aa3b, v56
	v_exp_f32_e32 v57, v57
	v_add_f32_e32 v16, v16, v76
	s_mov_b64 s[4:5], 0x12000
	v_lshl_add_u64 v[68:69], v[120:121], 0, s[4:5]
	v_add_f32_e32 v57, 1.0, v57
	v_rcp_f32_e32 v57, v57
	v_add_f32_e32 v12, v12, v79
	v_add_f32_e32 v13, v13, v77
	v_add_f32_e32 v14, v14, v78
	v_mul_f32_e32 v57, v149, v57
	v_cndmask_b32_e64 v81, v56, v57, s[2:3]
	v_add_f32_e32 v56, v58, v74
	v_mul_f32_e32 v57, 0xbfb8aa3b, v56
	v_exp_f32_e32 v57, v57
	v_add_f32_e32 v15, v15, v75
	v_add_f32_e32 v8, v8, v76
	s_mov_b64 s[4:5], 0x14000
	v_add_f32_e32 v57, 1.0, v57
	v_rcp_f32_e32 v57, v57
	v_lshl_add_u64 v[66:67], v[120:121], 0, s[4:5]
	v_add_f32_e32 v4, v4, v79
	v_add_f32_e32 v5, v5, v77
	v_mul_f32_e32 v57, v149, v57
	v_cndmask_b32_e64 v82, v56, v57, s[2:3]
	v_add_f32_e32 v56, v59, v72
	v_mul_f32_e32 v57, 0xbfb8aa3b, v56
	v_exp_f32_e32 v57, v57
	v_add_f32_e32 v6, v6, v78
	v_add_f32_e32 v7, v7, v75
	v_add_f32_e32 v0, v0, v76
	v_add_f32_e32 v57, 1.0, v57
	v_rcp_f32_e32 v57, v57
	s_mov_b64 s[4:5], 0x16000
	v_lshl_add_u64 v[64:65], v[120:121], 0, s[4:5]
	s_and_b64 vcc, exec, s[6:7]
	v_mul_f32_e32 v57, v149, v57
	v_cndmask_b32_e64 v59, v56, v57, s[2:3]
	v_cvt_pk_bf16_f32 v56, v60, v61
	v_cvt_pk_bf16_f32 v57, v62, v63
	v_cvt_pk_bf16_f32 v58, v80, v81
	v_cvt_pk_bf16_f32 v59, v82, v59
	ds_bpermute_b32 v244, v248, v56
	ds_bpermute_b32 v245, v248, v57
	ds_bpermute_b32 v246, v248, v58
	ds_bpermute_b32 v247, v248, v59
	v_ashrrev_i32_e32 v251, 31, v249
	v_add_co_u32_e64 v250, s[98:99], v120, v249
	s_nop 1
	v_addc_co_u32_e64 v251, s[98:99], v121, v251, s[98:99]
	s_waitcnt lgkmcnt(0)
	global_store_dwordx4 v[250:251], v[244:247], off offset:256
	s_nop 1
	v_mul_f32_e32 v56, 0xbfb8aa3b, v52
	v_exp_f32_e32 v56, v56
	s_nop 0
	v_add_f32_e32 v56, 1.0, v56
	v_rcp_f32_e32 v56, v56
	s_nop 0
	v_mul_f32_e32 v56, v149, v56
	v_cndmask_b32_e64 v52, v52, v56, s[2:3]
	v_mul_f32_e32 v56, 0xbfb8aa3b, v53
	v_exp_f32_e32 v56, v56
	s_nop 0
	v_add_f32_e32 v56, 1.0, v56
	v_rcp_f32_e32 v56, v56
	s_nop 0
	v_mul_f32_e32 v56, v149, v56
	v_cndmask_b32_e64 v53, v53, v56, s[2:3]
	v_mul_f32_e32 v56, 0xbfb8aa3b, v54
	v_exp_f32_e32 v56, v56
	s_nop 0
	v_add_f32_e32 v56, 1.0, v56
	v_rcp_f32_e32 v56, v56
	s_nop 0
	v_mul_f32_e32 v56, v149, v56
	v_cndmask_b32_e64 v54, v54, v56, s[2:3]
	v_mul_f32_e32 v56, 0xbfb8aa3b, v55
	v_exp_f32_e32 v56, v56
	s_nop 0
	v_add_f32_e32 v56, 1.0, v56
	v_rcp_f32_e32 v56, v56
	s_nop 0
	v_mul_f32_e32 v56, v149, v56
	v_cndmask_b32_e64 v55, v55, v56, s[2:3]
	v_mul_f32_e32 v56, 0xbfb8aa3b, v48
	v_exp_f32_e32 v56, v56
	s_nop 0
	v_add_f32_e32 v56, 1.0, v56
	v_rcp_f32_e32 v56, v56
	s_nop 0
	v_mul_f32_e32 v56, v149, v56
	v_cndmask_b32_e64 v56, v48, v56, s[2:3]
	v_add_f32_e32 v48, v49, v73
	v_mul_f32_e32 v49, 0xbfb8aa3b, v48
	v_exp_f32_e32 v49, v49
	s_nop 0
	v_add_f32_e32 v49, 1.0, v49
	v_rcp_f32_e32 v49, v49
	s_nop 0
	v_mul_f32_e32 v49, v149, v49
	v_cndmask_b32_e64 v57, v48, v49, s[2:3]
	v_add_f32_e32 v48, v50, v74
	v_mul_f32_e32 v49, 0xbfb8aa3b, v48
	v_exp_f32_e32 v49, v49
	s_nop 0
	v_add_f32_e32 v49, 1.0, v49
	v_rcp_f32_e32 v49, v49
	s_nop 0
	v_mul_f32_e32 v49, v149, v49
	v_cndmask_b32_e64 v58, v48, v49, s[2:3]
	v_add_f32_e32 v48, v51, v72
	v_mul_f32_e32 v49, 0xbfb8aa3b, v48
	v_exp_f32_e32 v49, v49
	s_nop 0
	v_add_f32_e32 v49, 1.0, v49
	v_rcp_f32_e32 v49, v49
	s_nop 0
	v_mul_f32_e32 v49, v149, v49
	v_cndmask_b32_e64 v51, v48, v49, s[2:3]
	v_cvt_pk_bf16_f32 v48, v52, v53
	v_cvt_pk_bf16_f32 v49, v54, v55
	v_cvt_pk_bf16_f32 v50, v56, v57
	v_cvt_pk_bf16_f32 v51, v58, v51
	ds_bpermute_b32 v244, v248, v48
	ds_bpermute_b32 v245, v248, v49
	ds_bpermute_b32 v246, v248, v50
	ds_bpermute_b32 v247, v248, v51
	v_ashrrev_i32_e32 v251, 31, v249
	v_add_co_u32_e64 v250, s[98:99], v112, v249
	s_nop 1
	v_addc_co_u32_e64 v251, s[98:99], v113, v251, s[98:99]
	s_waitcnt lgkmcnt(0)
; __device__ __forceinline__ unsigned cvt_pk_bf16(float lo, float hi) { unsigned r; asm volatile("v_cvt_pk_bf16_f32 %0, %1, %2" : "=v"(r) : "v"(lo), "v"(hi)); return r; }
;   DI void operator()(const pg8::f32x4 (&acc)[2][2][4][2], const pg8::Unit& u, int wr, int wc, int fr, int fq) const {
;     ...
;           float o[8];
; #pragma unroll
;           for (int n = 0; n < 2; ++n)
; #pragma unroll
;             for (int e = 0; e < 4; ++e) {
;               const float x = acc[ai][bj][m][n][e] + bias[n * 4 + e];
;               const float sg = osc * __builtin_amdgcn_rcpf(1.f + __expf(-x));
;               o[n * 4 + e] = (kind < 4) ? sg : x;
;             }
;           u32x4 w; w.x = pg8::cvt_pk_bf16(o[0], o[1]); w.y = pg8::cvt_pk_bf16(o[2], o[3]); w.z = pg8::cvt_pk_bf16(o[4], o[5]); w.w = pg8::cvt_pk_bf16(o[6], o[7]);
;           *(u32x4*)(base + (size_t)(row0 + ai * 128 + m * 16) * 256 + c0) = w;
	global_store_dwordx4 v[250:251], v[244:247], off offset:256
	s_nop 1
	v_mul_f32_e32 v48, 0xbfb8aa3b, v44
	v_exp_f32_e32 v48, v48
	s_nop 0
	v_add_f32_e32 v48, 1.0, v48
	v_rcp_f32_e32 v48, v48
	s_nop 0
	v_mul_f32_e32 v48, v149, v48
	v_cndmask_b32_e64 v44, v44, v48, s[2:3]
	v_mul_f32_e32 v48, 0xbfb8aa3b, v45
	v_exp_f32_e32 v48, v48
	s_nop 0
	v_add_f32_e32 v48, 1.0, v48
	v_rcp_f32_e32 v48, v48
	s_nop 0
	v_mul_f32_e32 v48, v149, v48
	v_cndmask_b32_e64 v45, v45, v48, s[2:3]
	v_mul_f32_e32 v48, 0xbfb8aa3b, v46
	v_exp_f32_e32 v48, v48
	s_nop 0
	v_add_f32_e32 v48, 1.0, v48
	v_rcp_f32_e32 v48, v48
	s_nop 0
	v_mul_f32_e32 v48, v149, v48
	v_cndmask_b32_e64 v46, v46, v48, s[2:3]
	v_mul_f32_e32 v48, 0xbfb8aa3b, v47
	v_exp_f32_e32 v48, v48
	s_nop 0
	v_add_f32_e32 v48, 1.0, v48
	v_rcp_f32_e32 v48, v48
	s_nop 0
	v_mul_f32_e32 v48, v149, v48
	v_cndmask_b32_e64 v47, v47, v48, s[2:3]
	v_mul_f32_e32 v48, 0xbfb8aa3b, v40
	v_exp_f32_e32 v48, v48
	s_nop 0
	v_add_f32_e32 v48, 1.0, v48
	v_rcp_f32_e32 v48, v48
	s_nop 0
	v_mul_f32_e32 v48, v149, v48
	v_cndmask_b32_e64 v48, v40, v48, s[2:3]
	v_add_f32_e32 v40, v41, v73
	v_mul_f32_e32 v41, 0xbfb8aa3b, v40
	v_exp_f32_e32 v41, v41
	s_nop 0
	v_add_f32_e32 v41, 1.0, v41
	v_rcp_f32_e32 v41, v41
	s_nop 0
	v_mul_f32_e32 v41, v149, v41
	v_cndmask_b32_e64 v49, v40, v41, s[2:3]
	v_add_f32_e32 v40, v42, v74
	v_mul_f32_e32 v41, 0xbfb8aa3b, v40
	v_exp_f32_e32 v41, v41
	s_nop 0
	v_add_f32_e32 v41, 1.0, v41
	v_rcp_f32_e32 v41, v41
	s_nop 0
	v_mul_f32_e32 v41, v149, v41
	v_cndmask_b32_e64 v50, v40, v41, s[2:3]
	v_add_f32_e32 v40, v43, v72
	v_mul_f32_e32 v41, 0xbfb8aa3b, v40
	v_exp_f32_e32 v41, v41
	s_nop 0
	v_add_f32_e32 v41, 1.0, v41
	v_rcp_f32_e32 v41, v41
	s_nop 0
	v_mul_f32_e32 v41, v149, v41
	v_cndmask_b32_e64 v43, v40, v41, s[2:3]
	v_cvt_pk_bf16_f32 v40, v44, v45
	v_cvt_pk_bf16_f32 v41, v46, v47
	v_cvt_pk_bf16_f32 v42, v48, v49
	v_cvt_pk_bf16_f32 v43, v50, v43
	ds_bpermute_b32 v244, v248, v40
	ds_bpermute_b32 v245, v248, v41
	ds_bpermute_b32 v246, v248, v42
	ds_bpermute_b32 v247, v248, v43
	v_ashrrev_i32_e32 v251, 31, v249
	v_add_co_u32_e64 v250, s[98:99], v104, v249
	s_nop 1
	v_addc_co_u32_e64 v251, s[98:99], v105, v251, s[98:99]
	s_waitcnt lgkmcnt(0)
	global_store_dwordx4 v[250:251], v[244:247], off offset:256
	s_nop 1
	v_mul_f32_e32 v40, 0xbfb8aa3b, v36
	v_exp_f32_e32 v40, v40
	s_nop 0
	v_add_f32_e32 v40, 1.0, v40
	v_rcp_f32_e32 v40, v40
	s_nop 0
	v_mul_f32_e32 v40, v149, v40
	v_cndmask_b32_e64 v36, v36, v40, s[2:3]
	v_mul_f32_e32 v40, 0xbfb8aa3b, v37
	v_exp_f32_e32 v40, v40
	s_nop 0
	v_add_f32_e32 v40, 1.0, v40
	v_rcp_f32_e32 v40, v40
	s_nop 0
	v_mul_f32_e32 v40, v149, v40
	v_cndmask_b32_e64 v37, v37, v40, s[2:3]
	v_mul_f32_e32 v40, 0xbfb8aa3b, v38
	v_exp_f32_e32 v40, v40
	s_nop 0
	v_add_f32_e32 v40, 1.0, v40
	v_rcp_f32_e32 v40, v40
	s_nop 0
	v_mul_f32_e32 v40, v149, v40
	v_cndmask_b32_e64 v38, v38, v40, s[2:3]
	v_mul_f32_e32 v40, 0xbfb8aa3b, v39
	v_exp_f32_e32 v40, v40
	s_nop 0
	v_add_f32_e32 v40, 1.0, v40
	v_rcp_f32_e32 v40, v40
	s_nop 0
	v_mul_f32_e32 v40, v149, v40
	v_cndmask_b32_e64 v39, v39, v40, s[2:3]
	v_mul_f32_e32 v40, 0xbfb8aa3b, v32
	v_exp_f32_e32 v40, v40
	s_nop 0
	v_add_f32_e32 v40, 1.0, v40
	v_rcp_f32_e32 v40, v40
	s_nop 0
	v_mul_f32_e32 v40, v149, v40
	v_cndmask_b32_e64 v40, v32, v40, s[2:3]
	v_add_f32_e32 v32, v33, v73
	v_mul_f32_e32 v33, 0xbfb8aa3b, v32
	v_exp_f32_e32 v33, v33
	s_nop 0
	v_add_f32_e32 v33, 1.0, v33
	v_rcp_f32_e32 v33, v33
	s_nop 0
	v_mul_f32_e32 v33, v149, v33
	v_cndmask_b32_e64 v41, v32, v33, s[2:3]
	v_add_f32_e32 v32, v34, v74
	v_mul_f32_e32 v33, 0xbfb8aa3b, v32
	v_exp_f32_e32 v33, v33
	s_nop 0
	v_add_f32_e32 v33, 1.0, v33
	v_rcp_f32_e32 v33, v33
	s_nop 0
	v_mul_f32_e32 v33, v149, v33
	v_cndmask_b32_e64 v42, v32, v33, s[2:3]
	v_add_f32_e32 v32, v35, v72
	v_mul_f32_e32 v33, 0xbfb8aa3b, v32
	v_exp_f32_e32 v33, v33
	s_nop 0
	v_add_f32_e32 v33, 1.0, v33
	v_rcp_f32_e32 v33, v33
	s_nop 0
	v_mul_f32_e32 v33, v149, v33
	v_cndmask_b32_e64 v35, v32, v33, s[2:3]
	v_cvt_pk_bf16_f32 v32, v36, v37
	v_cvt_pk_bf16_f32 v33, v38, v39
	v_cvt_pk_bf16_f32 v34, v40, v41
	v_cvt_pk_bf16_f32 v35, v42, v35
	ds_bpermute_b32 v244, v248, v32
	ds_bpermute_b32 v245, v248, v33
	ds_bpermute_b32 v246, v248, v34
	ds_bpermute_b32 v247, v248, v35
	v_ashrrev_i32_e32 v251, 31, v249
	v_add_co_u32_e64 v250, s[98:99], v96, v249
	s_nop 1
	v_addc_co_u32_e64 v251, s[98:99], v97, v251, s[98:99]
	s_waitcnt lgkmcnt(0)
	global_store_dwordx4 v[250:251], v[244:247], off offset:256
	s_nop 1
	v_mul_f32_e32 v32, 0xbfb8aa3b, v28
	v_exp_f32_e32 v32, v32
	s_nop 0
	v_add_f32_e32 v32, 1.0, v32
	v_rcp_f32_e32 v32, v32
	s_nop 0
	v_mul_f32_e32 v32, v149, v32
	v_cndmask_b32_e64 v28, v28, v32, s[2:3]
	v_mul_f32_e32 v32, 0xbfb8aa3b, v29
	v_exp_f32_e32 v32, v32
	s_nop 0
	v_add_f32_e32 v32, 1.0, v32
	v_rcp_f32_e32 v32, v32
	s_nop 0
	v_mul_f32_e32 v32, v149, v32
	v_cndmask_b32_e64 v29, v29, v32, s[2:3]
	v_mul_f32_e32 v32, 0xbfb8aa3b, v30
	v_exp_f32_e32 v32, v32
	s_nop 0
	v_add_f32_e32 v32, 1.0, v32
	v_rcp_f32_e32 v32, v32
	s_nop 0
	v_mul_f32_e32 v32, v149, v32
	v_cndmask_b32_e64 v30, v30, v32, s[2:3]
	v_mul_f32_e32 v32, 0xbfb8aa3b, v31
	v_exp_f32_e32 v32, v32
	s_nop 0
	v_add_f32_e32 v32, 1.0, v32
	v_rcp_f32_e32 v32, v32
	s_nop 0
	v_mul_f32_e32 v32, v149, v32
	v_cndmask_b32_e64 v31, v31, v32, s[2:3]
	v_mul_f32_e32 v32, 0xbfb8aa3b, v24
	v_exp_f32_e32 v32, v32
	s_nop 0
	v_add_f32_e32 v32, 1.0, v32
	v_rcp_f32_e32 v32, v32
	s_nop 0
	v_mul_f32_e32 v32, v149, v32
	v_cndmask_b32_e64 v32, v24, v32, s[2:3]
	v_add_f32_e32 v24, v25, v73
	v_mul_f32_e32 v25, 0xbfb8aa3b, v24
	v_exp_f32_e32 v25, v25
	s_nop 0
	v_add_f32_e32 v25, 1.0, v25
	v_rcp_f32_e32 v25, v25
	s_nop 0
	v_mul_f32_e32 v25, v149, v25
	v_cndmask_b32_e64 v33, v24, v25, s[2:3]
	v_add_f32_e32 v24, v26, v74
	v_mul_f32_e32 v25, 0xbfb8aa3b, v24
	v_exp_f32_e32 v25, v25
	s_nop 0
	v_add_f32_e32 v25, 1.0, v25
	v_rcp_f32_e32 v25, v25
	s_nop 0
	v_mul_f32_e32 v25, v149, v25
	v_cndmask_b32_e64 v34, v24, v25, s[2:3]
	v_add_f32_e32 v24, v27, v72
	v_mul_f32_e32 v25, 0xbfb8aa3b, v24
	v_exp_f32_e32 v25, v25
	s_nop 0
	v_add_f32_e32 v25, 1.0, v25
	v_rcp_f32_e32 v25, v25
	s_nop 0
	v_mul_f32_e32 v25, v149, v25
	v_cndmask_b32_e64 v27, v24, v25, s[2:3]
	v_cvt_pk_bf16_f32 v24, v28, v29
	v_cvt_pk_bf16_f32 v25, v30, v31
	v_cvt_pk_bf16_f32 v26, v32, v33
	v_cvt_pk_bf16_f32 v27, v34, v27
	ds_bpermute_b32 v244, v248, v24
	ds_bpermute_b32 v245, v248, v25
	ds_bpermute_b32 v246, v248, v26
	ds_bpermute_b32 v247, v248, v27
	v_ashrrev_i32_e32 v251, 31, v249
	v_add_co_u32_e64 v250, s[98:99], v70, v249
	s_nop 1
	v_addc_co_u32_e64 v251, s[98:99], v71, v251, s[98:99]
	s_waitcnt lgkmcnt(0)
; __device__ __forceinline__ unsigned cvt_pk_bf16(float lo, float hi) { unsigned r; asm volatile("v_cvt_pk_bf16_f32 %0, %1, %2" : "=v"(r) : "v"(lo), "v"(hi)); return r; }
; #define PG8_BAR __builtin_amdgcn_s_barrier()
; template <class Epi, class Sched, bool ALIGN_EPI = false, bool SP2 = false>
; __device__ __forceinline__ void gemm_phase(PG8_LAS unsigned char* lds, const Gemm g, const Sched& S, const Epi& E) {
;     ...
;         if (!has_next) break;
; #pragma unroll
;         for (int a = 0; a < 2; ++a)
; #pragma unroll
;             for (int b = 0; b < 2; ++b)
; #pragma unroll
;                 for (int m = 0; m < 4; ++m)
; #pragma unroll
;                     for (int n = 0; n < 2; ++n) acc[a][b][m][n] = (f32x4){0.f, 0.f, 0.f, 0.f};
;         cur = nxt; cA = nA; cB = nB; ++ui;
;         if constexpr (ALIGN_EPI) { if (wr == 1) PG8_BAR; }
;   DI void operator()(const pg8::f32x4 (&acc)[2][2][4][2], const pg8::Unit& u, int wr, int wc, int fr, int fq) const {
;     ...
;           float o[8];
; #pragma unroll
;           for (int n = 0; n < 2; ++n)
; #pragma unroll
;             for (int e = 0; e < 4; ++e) {
;               const float x = acc[ai][bj][m][n][e] + bias[n * 4 + e];
;               const float sg = osc * __builtin_amdgcn_rcpf(1.f + __expf(-x));
;               o[n * 4 + e] = (kind < 4) ? sg : x;
;             }
;           u32x4 w; w.x = pg8::cvt_pk_bf16(o[0], o[1]); w.y = pg8::cvt_pk_bf16(o[2], o[3]); w.z = pg8::cvt_pk_bf16(o[4], o[5]); w.w = pg8::cvt_pk_bf16(o[6], o[7]);
;           *(u32x4*)(base + (size_t)(row0 + ai * 128 + m * 16) * 256 + c0) = w;
	global_store_dwordx4 v[250:251], v[244:247], off offset:256
	s_nop 1
	v_mul_f32_e32 v24, 0xbfb8aa3b, v20
	v_exp_f32_e32 v24, v24
	s_nop 0
	v_add_f32_e32 v24, 1.0, v24
	v_rcp_f32_e32 v24, v24
	s_nop 0
	v_mul_f32_e32 v24, v149, v24
	v_cndmask_b32_e64 v20, v20, v24, s[2:3]
	v_mul_f32_e32 v24, 0xbfb8aa3b, v21
	v_exp_f32_e32 v24, v24
	s_nop 0
	v_add_f32_e32 v24, 1.0, v24
	v_rcp_f32_e32 v24, v24
	s_nop 0
	v_mul_f32_e32 v24, v149, v24
	v_cndmask_b32_e64 v21, v21, v24, s[2:3]
	v_mul_f32_e32 v24, 0xbfb8aa3b, v22
	v_exp_f32_e32 v24, v24
	s_nop 0
	v_add_f32_e32 v24, 1.0, v24
	v_rcp_f32_e32 v24, v24
	s_nop 0
	v_mul_f32_e32 v24, v149, v24
	v_cndmask_b32_e64 v22, v22, v24, s[2:3]
	v_mul_f32_e32 v24, 0xbfb8aa3b, v23
	v_exp_f32_e32 v24, v24
	s_nop 0
	v_add_f32_e32 v24, 1.0, v24
	v_rcp_f32_e32 v24, v24
	s_nop 0
	v_mul_f32_e32 v24, v149, v24
	v_cndmask_b32_e64 v23, v23, v24, s[2:3]
	v_mul_f32_e32 v24, 0xbfb8aa3b, v16
	v_exp_f32_e32 v24, v24
	s_nop 0
	v_add_f32_e32 v24, 1.0, v24
	v_rcp_f32_e32 v24, v24
	s_nop 0
	v_mul_f32_e32 v24, v149, v24
	v_cndmask_b32_e64 v24, v16, v24, s[2:3]
	v_add_f32_e32 v16, v17, v73
	v_mul_f32_e32 v17, 0xbfb8aa3b, v16
	v_exp_f32_e32 v17, v17
	s_nop 0
	v_add_f32_e32 v17, 1.0, v17
	v_rcp_f32_e32 v17, v17
	s_nop 0
	v_mul_f32_e32 v17, v149, v17
	v_cndmask_b32_e64 v25, v16, v17, s[2:3]
	v_add_f32_e32 v16, v18, v74
	v_mul_f32_e32 v17, 0xbfb8aa3b, v16
	v_exp_f32_e32 v17, v17
	s_nop 0
	v_add_f32_e32 v17, 1.0, v17
	v_rcp_f32_e32 v17, v17
	s_nop 0
	v_mul_f32_e32 v17, v149, v17
	v_cndmask_b32_e64 v26, v16, v17, s[2:3]
	v_add_f32_e32 v16, v19, v72
	v_mul_f32_e32 v17, 0xbfb8aa3b, v16
	v_exp_f32_e32 v17, v17
	s_nop 0
	v_add_f32_e32 v17, 1.0, v17
	v_rcp_f32_e32 v17, v17
	s_nop 0
	v_mul_f32_e32 v17, v149, v17
	v_cndmask_b32_e64 v19, v16, v17, s[2:3]
	v_cvt_pk_bf16_f32 v16, v20, v21
	v_cvt_pk_bf16_f32 v17, v22, v23
	v_cvt_pk_bf16_f32 v18, v24, v25
	v_cvt_pk_bf16_f32 v19, v26, v19
	ds_bpermute_b32 v244, v248, v16
	ds_bpermute_b32 v245, v248, v17
	ds_bpermute_b32 v246, v248, v18
	ds_bpermute_b32 v247, v248, v19
	v_ashrrev_i32_e32 v251, 31, v249
	v_add_co_u32_e64 v250, s[98:99], v68, v249
	s_nop 1
	v_addc_co_u32_e64 v251, s[98:99], v69, v251, s[98:99]
	s_waitcnt lgkmcnt(0)
	global_store_dwordx4 v[250:251], v[244:247], off offset:256
	s_nop 1
	v_mul_f32_e32 v16, 0xbfb8aa3b, v12
	v_exp_f32_e32 v16, v16
	s_nop 0
	v_add_f32_e32 v16, 1.0, v16
	v_rcp_f32_e32 v16, v16
	s_nop 0
	v_mul_f32_e32 v16, v149, v16
	v_cndmask_b32_e64 v12, v12, v16, s[2:3]
	v_mul_f32_e32 v16, 0xbfb8aa3b, v13
	v_exp_f32_e32 v16, v16
	s_nop 0
	v_add_f32_e32 v16, 1.0, v16
	v_rcp_f32_e32 v16, v16
	s_nop 0
	v_mul_f32_e32 v16, v149, v16
	v_cndmask_b32_e64 v13, v13, v16, s[2:3]
	v_mul_f32_e32 v16, 0xbfb8aa3b, v14
	v_exp_f32_e32 v16, v16
	s_nop 0
	v_add_f32_e32 v16, 1.0, v16
	v_rcp_f32_e32 v16, v16
	s_nop 0
	v_mul_f32_e32 v16, v149, v16
	v_cndmask_b32_e64 v14, v14, v16, s[2:3]
	v_mul_f32_e32 v16, 0xbfb8aa3b, v15
	v_exp_f32_e32 v16, v16
	s_nop 0
	v_add_f32_e32 v16, 1.0, v16
	v_rcp_f32_e32 v16, v16
	s_nop 0
	v_mul_f32_e32 v16, v149, v16
	v_cndmask_b32_e64 v15, v15, v16, s[2:3]
	v_mul_f32_e32 v16, 0xbfb8aa3b, v8
	v_exp_f32_e32 v16, v16
	s_nop 0
	v_add_f32_e32 v16, 1.0, v16
	v_rcp_f32_e32 v16, v16
	s_nop 0
	v_mul_f32_e32 v16, v149, v16
	v_cndmask_b32_e64 v16, v8, v16, s[2:3]
	v_add_f32_e32 v8, v9, v73
	v_mul_f32_e32 v9, 0xbfb8aa3b, v8
	v_exp_f32_e32 v9, v9
	s_nop 0
	v_add_f32_e32 v9, 1.0, v9
	v_rcp_f32_e32 v9, v9
	s_nop 0
	v_mul_f32_e32 v9, v149, v9
	v_cndmask_b32_e64 v17, v8, v9, s[2:3]
	v_add_f32_e32 v8, v10, v74
	v_mul_f32_e32 v9, 0xbfb8aa3b, v8
	v_exp_f32_e32 v9, v9
	s_nop 0
	v_add_f32_e32 v9, 1.0, v9
	v_rcp_f32_e32 v9, v9
	s_nop 0
	v_mul_f32_e32 v9, v149, v9
	v_cndmask_b32_e64 v18, v8, v9, s[2:3]
	v_add_f32_e32 v8, v11, v72
	v_mul_f32_e32 v9, 0xbfb8aa3b, v8
	v_exp_f32_e32 v9, v9
	s_nop 0
	v_add_f32_e32 v9, 1.0, v9
	v_rcp_f32_e32 v9, v9
	s_nop 0
	v_mul_f32_e32 v9, v149, v9
	v_cndmask_b32_e64 v11, v8, v9, s[2:3]
	v_cvt_pk_bf16_f32 v8, v12, v13
	v_cvt_pk_bf16_f32 v9, v14, v15
	v_cvt_pk_bf16_f32 v10, v16, v17
	v_cvt_pk_bf16_f32 v11, v18, v11
	ds_bpermute_b32 v244, v248, v8
	ds_bpermute_b32 v245, v248, v9
	ds_bpermute_b32 v246, v248, v10
	ds_bpermute_b32 v247, v248, v11
	v_ashrrev_i32_e32 v251, 31, v249
	v_add_co_u32_e64 v250, s[98:99], v66, v249
	s_nop 1
	v_addc_co_u32_e64 v251, s[98:99], v67, v251, s[98:99]
	s_waitcnt lgkmcnt(0)
	global_store_dwordx4 v[250:251], v[244:247], off offset:256
	s_nop 1
	v_mul_f32_e32 v8, 0xbfb8aa3b, v4
	v_exp_f32_e32 v8, v8
	s_nop 0
	v_add_f32_e32 v8, 1.0, v8
	v_rcp_f32_e32 v8, v8
	s_nop 0
	v_mul_f32_e32 v8, v149, v8
	v_cndmask_b32_e64 v4, v4, v8, s[2:3]
	v_mul_f32_e32 v8, 0xbfb8aa3b, v5
	v_exp_f32_e32 v8, v8
	s_nop 0
	v_add_f32_e32 v8, 1.0, v8
	v_rcp_f32_e32 v8, v8
	s_nop 0
	v_mul_f32_e32 v8, v149, v8
	v_cndmask_b32_e64 v5, v5, v8, s[2:3]
	v_mul_f32_e32 v8, 0xbfb8aa3b, v6
	v_exp_f32_e32 v8, v8
	s_nop 0
	v_add_f32_e32 v8, 1.0, v8
	v_rcp_f32_e32 v8, v8
	s_nop 0
	v_mul_f32_e32 v8, v149, v8
	v_cndmask_b32_e64 v6, v6, v8, s[2:3]
	v_mul_f32_e32 v8, 0xbfb8aa3b, v7
	v_exp_f32_e32 v8, v8
	s_nop 0
	v_add_f32_e32 v8, 1.0, v8
	v_rcp_f32_e32 v8, v8
	s_nop 0
	v_mul_f32_e32 v8, v149, v8
	v_cndmask_b32_e64 v7, v7, v8, s[2:3]
	v_mul_f32_e32 v8, 0xbfb8aa3b, v0
	v_exp_f32_e32 v8, v8
	s_nop 0
	v_add_f32_e32 v8, 1.0, v8
	v_rcp_f32_e32 v8, v8
	s_nop 0
	v_mul_f32_e32 v8, v149, v8
	v_cndmask_b32_e64 v8, v0, v8, s[2:3]
	v_add_f32_e32 v0, v1, v73
	v_mul_f32_e32 v1, 0xbfb8aa3b, v0
	v_exp_f32_e32 v1, v1
	s_nop 0
	v_add_f32_e32 v1, 1.0, v1
	v_rcp_f32_e32 v1, v1
	s_nop 0
	v_mul_f32_e32 v1, v149, v1
	v_cndmask_b32_e64 v9, v0, v1, s[2:3]
	v_add_f32_e32 v0, v2, v74
	v_mul_f32_e32 v1, 0xbfb8aa3b, v0
	v_exp_f32_e32 v1, v1
	s_nop 0
	v_add_f32_e32 v1, 1.0, v1
	v_rcp_f32_e32 v1, v1
	s_nop 0
	v_mul_f32_e32 v1, v149, v1
	v_cndmask_b32_e64 v10, v0, v1, s[2:3]
	v_add_f32_e32 v0, v3, v72
	v_mul_f32_e32 v1, 0xbfb8aa3b, v0
	v_exp_f32_e32 v1, v1
	s_nop 0
	v_add_f32_e32 v1, 1.0, v1
	v_rcp_f32_e32 v1, v1
	s_nop 0
	v_mul_f32_e32 v1, v149, v1
	v_cndmask_b32_e64 v3, v0, v1, s[2:3]
	s_mov_b64 s[2:3], -1
	v_cvt_pk_bf16_f32 v0, v4, v5
	v_cvt_pk_bf16_f32 v1, v6, v7
	v_cvt_pk_bf16_f32 v2, v8, v9
	v_cvt_pk_bf16_f32 v3, v10, v3
	ds_bpermute_b32 v244, v248, v0
	ds_bpermute_b32 v245, v248, v1
	ds_bpermute_b32 v246, v248, v2
	ds_bpermute_b32 v247, v248, v3
	v_ashrrev_i32_e32 v251, 31, v249
	v_add_co_u32_e64 v250, s[98:99], v64, v249
	s_nop 1
	v_addc_co_u32_e64 v251, s[98:99], v65, v251, s[98:99]
	s_waitcnt lgkmcnt(0)
	global_store_dwordx4 v[250:251], v[244:247], off offset:256
	s_cbranch_vccnz .LBB0_329
	s_andn2_b64 vcc, exec, s[14:15]
	s_cbranch_vccnz .LBB0_328
	s_barrier
	s_branch .LBB0_328
